# P3 pool-GEMM and P4 (EpiGate) epilogues rewritten by hand with the same lane permutation / coalesced loads+stores as P7
# baseline (speedup 1.0000x reference)
.LBB0_481:
	v_and_b32_e32 v166, 3, v209
	v_bfe_u32 v167, v209, 4, 2
	v_and_or_b32 v167, v209, 12, v167
	v_lshl_or_b32 v150, v166, 4, v167
	v_lshlrev_b32_e32 v150, 2, v150
	v_and_or_b32 v167, v155, -16, v167
	v_and_b32_e32 v168, 0x60, v157
	v_lshl_or_b32 v168, v166, 3, v168
	v_lshl_add_u32 v167, s84, 8, v167
	v_lshl_or_b32 v168, s85, 8, v168
	v_lshlrev_b32_e32 v167, 11, v167
	v_lshl_add_u32 v188, v168, 1, v167
	v_mov_b32_e32 v144, v188
	v_lshrrev_b32_e32 v145, 1, v144
	global_load_dwordx2 v[172:173], v145, s[30:31]
	global_load_dwordx2 v[174:175], v145, s[30:31] offset:128
	v_add_u32_e32 v146, 0x8000, v188
	v_lshrrev_b32_e32 v147, 1, v146
	global_load_dwordx2 v[176:177], v147, s[30:31]
	global_load_dwordx2 v[178:179], v147, s[30:31] offset:128
	v_add_u32_e32 v144, 0x10000, v188
	v_lshrrev_b32_e32 v145, 1, v144
	global_load_dwordx2 v[180:181], v145, s[30:31]
	global_load_dwordx2 v[182:183], v145, s[30:31] offset:128
	v_add_u32_e32 v146, 0x18000, v188
	v_lshrrev_b32_e32 v147, 1, v146
	global_load_dwordx2 v[184:185], v147, s[30:31]
	global_load_dwordx2 v[186:187], v147, s[30:31] offset:128
	ds_bpermute_b32 v124, v150, v124
	ds_bpermute_b32 v125, v150, v125
	ds_bpermute_b32 v126, v150, v126
	ds_bpermute_b32 v127, v150, v127
	ds_bpermute_b32 v120, v150, v120
	ds_bpermute_b32 v121, v150, v121
	ds_bpermute_b32 v122, v150, v122
	ds_bpermute_b32 v123, v150, v123
	ds_bpermute_b32 v108, v150, v108
	ds_bpermute_b32 v109, v150, v109
	ds_bpermute_b32 v110, v150, v110
	ds_bpermute_b32 v111, v150, v111
	ds_bpermute_b32 v104, v150, v104
	ds_bpermute_b32 v105, v150, v105
	ds_bpermute_b32 v106, v150, v106
	ds_bpermute_b32 v107, v150, v107
	ds_bpermute_b32 v92, v150, v92
	ds_bpermute_b32 v93, v150, v93
	ds_bpermute_b32 v94, v150, v94
	ds_bpermute_b32 v95, v150, v95
	ds_bpermute_b32 v88, v150, v88
	ds_bpermute_b32 v89, v150, v89
	ds_bpermute_b32 v90, v150, v90
	ds_bpermute_b32 v91, v150, v91
	ds_bpermute_b32 v76, v150, v76
	ds_bpermute_b32 v77, v150, v77
	ds_bpermute_b32 v78, v150, v78
	ds_bpermute_b32 v79, v150, v79
	ds_bpermute_b32 v72, v150, v72
	ds_bpermute_b32 v73, v150, v73
	ds_bpermute_b32 v74, v150, v74
	ds_bpermute_b32 v75, v150, v75
	s_and_b64 vcc, exec, s[40:41]
	s_cbranch_vccz .Lp3_nb
	s_barrier
.Lp3_nb:
	ds_bpermute_b32 v116, v150, v116
	ds_bpermute_b32 v117, v150, v117
	ds_bpermute_b32 v118, v150, v118
	ds_bpermute_b32 v119, v150, v119
	ds_bpermute_b32 v112, v150, v112
	ds_bpermute_b32 v113, v150, v113
	ds_bpermute_b32 v114, v150, v114
	ds_bpermute_b32 v115, v150, v115
	ds_bpermute_b32 v100, v150, v100
	ds_bpermute_b32 v101, v150, v101
	ds_bpermute_b32 v102, v150, v102
	ds_bpermute_b32 v103, v150, v103
	ds_bpermute_b32 v96, v150, v96
	ds_bpermute_b32 v97, v150, v97
	ds_bpermute_b32 v98, v150, v98
	ds_bpermute_b32 v99, v150, v99
	ds_bpermute_b32 v84, v150, v84
	ds_bpermute_b32 v85, v150, v85
	ds_bpermute_b32 v86, v150, v86
	ds_bpermute_b32 v87, v150, v87
	ds_bpermute_b32 v80, v150, v80
	ds_bpermute_b32 v81, v150, v81
	ds_bpermute_b32 v82, v150, v82
	ds_bpermute_b32 v83, v150, v83
	ds_bpermute_b32 v68, v150, v68
	ds_bpermute_b32 v69, v150, v69
	ds_bpermute_b32 v70, v150, v70
	ds_bpermute_b32 v71, v150, v71
	ds_bpermute_b32 v64, v150, v64
	ds_bpermute_b32 v65, v150, v65
	ds_bpermute_b32 v66, v150, v66
	ds_bpermute_b32 v67, v150, v67
	ds_bpermute_b32 v60, v150, v60
	ds_bpermute_b32 v61, v150, v61
	ds_bpermute_b32 v62, v150, v62
	ds_bpermute_b32 v63, v150, v63
	ds_bpermute_b32 v56, v150, v56
	ds_bpermute_b32 v57, v150, v57
	ds_bpermute_b32 v58, v150, v58
	ds_bpermute_b32 v59, v150, v59
	ds_bpermute_b32 v44, v150, v44
	ds_bpermute_b32 v45, v150, v45
	ds_bpermute_b32 v46, v150, v46
	ds_bpermute_b32 v47, v150, v47
	ds_bpermute_b32 v40, v150, v40
	ds_bpermute_b32 v41, v150, v41
	ds_bpermute_b32 v42, v150, v42
	ds_bpermute_b32 v43, v150, v43
	ds_bpermute_b32 v28, v150, v28
	ds_bpermute_b32 v29, v150, v29
	ds_bpermute_b32 v30, v150, v30
	ds_bpermute_b32 v31, v150, v31
	ds_bpermute_b32 v24, v150, v24
	ds_bpermute_b32 v25, v150, v25
	ds_bpermute_b32 v26, v150, v26
	ds_bpermute_b32 v27, v150, v27
	ds_bpermute_b32 v12, v150, v12
	ds_bpermute_b32 v13, v150, v13
	ds_bpermute_b32 v14, v150, v14
	ds_bpermute_b32 v15, v150, v15
	ds_bpermute_b32 v8, v150, v8
	ds_bpermute_b32 v9, v150, v9
	ds_bpermute_b32 v10, v150, v10
	ds_bpermute_b32 v11, v150, v11
	ds_bpermute_b32 v52, v150, v52
	ds_bpermute_b32 v53, v150, v53
	ds_bpermute_b32 v54, v150, v54
	ds_bpermute_b32 v55, v150, v55
	ds_bpermute_b32 v48, v150, v48
	ds_bpermute_b32 v49, v150, v49
	ds_bpermute_b32 v50, v150, v50
	ds_bpermute_b32 v51, v150, v51
	ds_bpermute_b32 v36, v150, v36
	ds_bpermute_b32 v37, v150, v37
	ds_bpermute_b32 v38, v150, v38
	ds_bpermute_b32 v39, v150, v39
	ds_bpermute_b32 v32, v150, v32
	ds_bpermute_b32 v33, v150, v33
	ds_bpermute_b32 v34, v150, v34
	ds_bpermute_b32 v35, v150, v35
	ds_bpermute_b32 v20, v150, v20
	ds_bpermute_b32 v21, v150, v21
	ds_bpermute_b32 v22, v150, v22
	ds_bpermute_b32 v23, v150, v23
	ds_bpermute_b32 v16, v150, v16
	ds_bpermute_b32 v17, v150, v17
	ds_bpermute_b32 v18, v150, v18
	ds_bpermute_b32 v19, v150, v19
	ds_bpermute_b32 v4, v150, v4
	ds_bpermute_b32 v5, v150, v5
	ds_bpermute_b32 v6, v150, v6
	ds_bpermute_b32 v7, v150, v7
	ds_bpermute_b32 v0, v150, v0
	ds_bpermute_b32 v1, v150, v1
	ds_bpermute_b32 v2, v150, v2
	ds_bpermute_b32 v3, v150, v3
	s_waitcnt lgkmcnt(0)
	s_waitcnt vmcnt(6)
	v_mov_b32_e32 v148, v188
	v_cvt_f32_ubyte0_e32 v162, v172
	v_cvt_f32_ubyte1_e32 v163, v172
	v_cvt_f32_ubyte2_e32 v164, v172
	v_cvt_f32_ubyte3_e32 v165, v172
	v_pk_mul_f32 v[162:163], v[162:163], s[48:49] op_sel_hi:[1,0]
	v_pk_mul_f32 v[164:165], v[164:165], s[48:49] op_sel_hi:[1,0]
	v_pk_mul_f32 v[124:125], v[124:125], v[162:163]
	v_pk_mul_f32 v[126:127], v[126:127], v[164:165]
	v_cvt_f32_ubyte0_e32 v162, v173
	v_cvt_f32_ubyte1_e32 v163, v173
	v_cvt_f32_ubyte2_e32 v164, v173
	v_cvt_f32_ubyte3_e32 v165, v173
	v_pk_mul_f32 v[162:163], v[162:163], s[48:49] op_sel_hi:[1,0]
	v_pk_mul_f32 v[164:165], v[164:165], s[48:49] op_sel_hi:[1,0]
	v_pk_mul_f32 v[120:121], v[120:121], v[162:163]
	v_pk_mul_f32 v[122:123], v[122:123], v[164:165]
	v_cvt_pk_bf16_f32 v124, v124, v125
	v_cvt_pk_bf16_f32 v125, v126, v127
	v_cvt_pk_bf16_f32 v126, v120, v121
	v_cvt_pk_bf16_f32 v127, v122, v123
	global_store_dwordx4 v148, v[124:127], s[20:21]
	v_cvt_f32_ubyte0_e32 v162, v174
	v_cvt_f32_ubyte1_e32 v163, v174
	v_cvt_f32_ubyte2_e32 v164, v174
	v_cvt_f32_ubyte3_e32 v165, v174
	v_pk_mul_f32 v[162:163], v[162:163], s[48:49] op_sel_hi:[1,0]
	v_pk_mul_f32 v[164:165], v[164:165], s[48:49] op_sel_hi:[1,0]
	v_pk_mul_f32 v[116:117], v[116:117], v[162:163]
	v_pk_mul_f32 v[118:119], v[118:119], v[164:165]
	v_cvt_f32_ubyte0_e32 v162, v175
	v_cvt_f32_ubyte1_e32 v163, v175
	v_cvt_f32_ubyte2_e32 v164, v175
	v_cvt_f32_ubyte3_e32 v165, v175
	v_pk_mul_f32 v[162:163], v[162:163], s[48:49] op_sel_hi:[1,0]
	v_pk_mul_f32 v[164:165], v[164:165], s[48:49] op_sel_hi:[1,0]
	v_pk_mul_f32 v[112:113], v[112:113], v[162:163]
	v_pk_mul_f32 v[114:115], v[114:115], v[164:165]
	v_cvt_pk_bf16_f32 v116, v116, v117
	v_cvt_pk_bf16_f32 v117, v118, v119
	v_cvt_pk_bf16_f32 v118, v112, v113
	v_cvt_pk_bf16_f32 v119, v114, v115
	global_store_dwordx4 v148, v[116:119], s[20:21] offset:256
	v_add_u32_e32 v144, 0x40000, v188
	v_lshrrev_b32_e32 v145, 1, v144
	global_load_dwordx2 v[172:173], v145, s[30:31]
	global_load_dwordx2 v[174:175], v145, s[30:31] offset:128
	s_waitcnt vmcnt(8)
	v_add_u32_e32 v149, 0x8000, v188
	v_cvt_f32_ubyte0_e32 v162, v176
	v_cvt_f32_ubyte1_e32 v163, v176
	v_cvt_f32_ubyte2_e32 v164, v176
	v_cvt_f32_ubyte3_e32 v165, v176
	v_pk_mul_f32 v[162:163], v[162:163], s[48:49] op_sel_hi:[1,0]
	v_pk_mul_f32 v[164:165], v[164:165], s[48:49] op_sel_hi:[1,0]
	v_pk_mul_f32 v[108:109], v[108:109], v[162:163]
	v_pk_mul_f32 v[110:111], v[110:111], v[164:165]
	v_cvt_f32_ubyte0_e32 v162, v177
	v_cvt_f32_ubyte1_e32 v163, v177
	v_cvt_f32_ubyte2_e32 v164, v177
	v_cvt_f32_ubyte3_e32 v165, v177
	v_pk_mul_f32 v[162:163], v[162:163], s[48:49] op_sel_hi:[1,0]
	v_pk_mul_f32 v[164:165], v[164:165], s[48:49] op_sel_hi:[1,0]
	v_pk_mul_f32 v[104:105], v[104:105], v[162:163]
	v_pk_mul_f32 v[106:107], v[106:107], v[164:165]
	v_cvt_pk_bf16_f32 v108, v108, v109
	v_cvt_pk_bf16_f32 v109, v110, v111
	v_cvt_pk_bf16_f32 v110, v104, v105
	v_cvt_pk_bf16_f32 v111, v106, v107
	global_store_dwordx4 v149, v[108:111], s[20:21]
	v_cvt_f32_ubyte0_e32 v162, v178
	v_cvt_f32_ubyte1_e32 v163, v178
	v_cvt_f32_ubyte2_e32 v164, v178
	v_cvt_f32_ubyte3_e32 v165, v178
	v_pk_mul_f32 v[162:163], v[162:163], s[48:49] op_sel_hi:[1,0]
	v_pk_mul_f32 v[164:165], v[164:165], s[48:49] op_sel_hi:[1,0]
	v_pk_mul_f32 v[100:101], v[100:101], v[162:163]
	v_pk_mul_f32 v[102:103], v[102:103], v[164:165]
	v_cvt_f32_ubyte0_e32 v162, v179
	v_cvt_f32_ubyte1_e32 v163, v179
	v_cvt_f32_ubyte2_e32 v164, v179
	v_cvt_f32_ubyte3_e32 v165, v179
	v_pk_mul_f32 v[162:163], v[162:163], s[48:49] op_sel_hi:[1,0]
	v_pk_mul_f32 v[164:165], v[164:165], s[48:49] op_sel_hi:[1,0]
	v_pk_mul_f32 v[96:97], v[96:97], v[162:163]
	v_pk_mul_f32 v[98:99], v[98:99], v[164:165]
	v_cvt_pk_bf16_f32 v100, v100, v101
	v_cvt_pk_bf16_f32 v101, v102, v103
	v_cvt_pk_bf16_f32 v102, v96, v97
	v_cvt_pk_bf16_f32 v103, v98, v99
	global_store_dwordx4 v149, v[100:103], s[20:21] offset:256
	v_add_u32_e32 v146, 0x48000, v188
	v_lshrrev_b32_e32 v147, 1, v146
	global_load_dwordx2 v[176:177], v147, s[30:31]
	global_load_dwordx2 v[178:179], v147, s[30:31] offset:128
	s_waitcnt vmcnt(10)
	v_add_u32_e32 v148, 0x10000, v188
	v_cvt_f32_ubyte0_e32 v162, v180
	v_cvt_f32_ubyte1_e32 v163, v180
	v_cvt_f32_ubyte2_e32 v164, v180
	v_cvt_f32_ubyte3_e32 v165, v180
	v_pk_mul_f32 v[162:163], v[162:163], s[48:49] op_sel_hi:[1,0]
	v_pk_mul_f32 v[164:165], v[164:165], s[48:49] op_sel_hi:[1,0]
	v_pk_mul_f32 v[92:93], v[92:93], v[162:163]
	v_pk_mul_f32 v[94:95], v[94:95], v[164:165]
	v_cvt_f32_ubyte0_e32 v162, v181
	v_cvt_f32_ubyte1_e32 v163, v181
	v_cvt_f32_ubyte2_e32 v164, v181
	v_cvt_f32_ubyte3_e32 v165, v181
	v_pk_mul_f32 v[162:163], v[162:163], s[48:49] op_sel_hi:[1,0]
	v_pk_mul_f32 v[164:165], v[164:165], s[48:49] op_sel_hi:[1,0]
	v_pk_mul_f32 v[88:89], v[88:89], v[162:163]
	v_pk_mul_f32 v[90:91], v[90:91], v[164:165]
	v_cvt_pk_bf16_f32 v92, v92, v93
	v_cvt_pk_bf16_f32 v93, v94, v95
	v_cvt_pk_bf16_f32 v94, v88, v89
	v_cvt_pk_bf16_f32 v95, v90, v91
	global_store_dwordx4 v148, v[92:95], s[20:21]
	v_cvt_f32_ubyte0_e32 v162, v182
	v_cvt_f32_ubyte1_e32 v163, v182
	v_cvt_f32_ubyte2_e32 v164, v182
	v_cvt_f32_ubyte3_e32 v165, v182
	v_pk_mul_f32 v[162:163], v[162:163], s[48:49] op_sel_hi:[1,0]
	v_pk_mul_f32 v[164:165], v[164:165], s[48:49] op_sel_hi:[1,0]
	v_pk_mul_f32 v[84:85], v[84:85], v[162:163]
	v_pk_mul_f32 v[86:87], v[86:87], v[164:165]
	v_cvt_f32_ubyte0_e32 v162, v183
	v_cvt_f32_ubyte1_e32 v163, v183
	v_cvt_f32_ubyte2_e32 v164, v183
	v_cvt_f32_ubyte3_e32 v165, v183
	v_pk_mul_f32 v[162:163], v[162:163], s[48:49] op_sel_hi:[1,0]
	v_pk_mul_f32 v[164:165], v[164:165], s[48:49] op_sel_hi:[1,0]
	v_pk_mul_f32 v[80:81], v[80:81], v[162:163]
	v_pk_mul_f32 v[82:83], v[82:83], v[164:165]
	v_cvt_pk_bf16_f32 v84, v84, v85
	v_cvt_pk_bf16_f32 v85, v86, v87
	v_cvt_pk_bf16_f32 v86, v80, v81
	v_cvt_pk_bf16_f32 v87, v82, v83
	global_store_dwordx4 v148, v[84:87], s[20:21] offset:256
	v_add_u32_e32 v144, 0x50000, v188
	v_lshrrev_b32_e32 v145, 1, v144
	global_load_dwordx2 v[180:181], v145, s[30:31]
	global_load_dwordx2 v[182:183], v145, s[30:31] offset:128
	s_waitcnt vmcnt(12)
	v_add_u32_e32 v149, 0x18000, v188
	v_cvt_f32_ubyte0_e32 v162, v184
	v_cvt_f32_ubyte1_e32 v163, v184
	v_cvt_f32_ubyte2_e32 v164, v184
	v_cvt_f32_ubyte3_e32 v165, v184
	v_pk_mul_f32 v[162:163], v[162:163], s[48:49] op_sel_hi:[1,0]
	v_pk_mul_f32 v[164:165], v[164:165], s[48:49] op_sel_hi:[1,0]
	v_pk_mul_f32 v[76:77], v[76:77], v[162:163]
	v_pk_mul_f32 v[78:79], v[78:79], v[164:165]
	v_cvt_f32_ubyte0_e32 v162, v185
	v_cvt_f32_ubyte1_e32 v163, v185
	v_cvt_f32_ubyte2_e32 v164, v185
	v_cvt_f32_ubyte3_e32 v165, v185
	v_pk_mul_f32 v[162:163], v[162:163], s[48:49] op_sel_hi:[1,0]
	v_pk_mul_f32 v[164:165], v[164:165], s[48:49] op_sel_hi:[1,0]
	v_pk_mul_f32 v[72:73], v[72:73], v[162:163]
	v_pk_mul_f32 v[74:75], v[74:75], v[164:165]
	v_cvt_pk_bf16_f32 v76, v76, v77
	v_cvt_pk_bf16_f32 v77, v78, v79
	v_cvt_pk_bf16_f32 v78, v72, v73
	v_cvt_pk_bf16_f32 v79, v74, v75
	global_store_dwordx4 v149, v[76:79], s[20:21]
	v_cvt_f32_ubyte0_e32 v162, v186
	v_cvt_f32_ubyte1_e32 v163, v186
	v_cvt_f32_ubyte2_e32 v164, v186
	v_cvt_f32_ubyte3_e32 v165, v186
	v_pk_mul_f32 v[162:163], v[162:163], s[48:49] op_sel_hi:[1,0]
	v_pk_mul_f32 v[164:165], v[164:165], s[48:49] op_sel_hi:[1,0]
	v_pk_mul_f32 v[68:69], v[68:69], v[162:163]
	v_pk_mul_f32 v[70:71], v[70:71], v[164:165]
	v_cvt_f32_ubyte0_e32 v162, v187
	v_cvt_f32_ubyte1_e32 v163, v187
	v_cvt_f32_ubyte2_e32 v164, v187
	v_cvt_f32_ubyte3_e32 v165, v187
	v_pk_mul_f32 v[162:163], v[162:163], s[48:49] op_sel_hi:[1,0]
	v_pk_mul_f32 v[164:165], v[164:165], s[48:49] op_sel_hi:[1,0]
	v_pk_mul_f32 v[64:65], v[64:65], v[162:163]
	v_pk_mul_f32 v[66:67], v[66:67], v[164:165]
	v_cvt_pk_bf16_f32 v68, v68, v69
	v_cvt_pk_bf16_f32 v69, v70, v71
	v_cvt_pk_bf16_f32 v70, v64, v65
	v_cvt_pk_bf16_f32 v71, v66, v67
	global_store_dwordx4 v149, v[68:71], s[20:21] offset:256
	v_add_u32_e32 v146, 0x58000, v188
	v_lshrrev_b32_e32 v147, 1, v146
	global_load_dwordx2 v[184:185], v147, s[30:31]
	global_load_dwordx2 v[186:187], v147, s[30:31] offset:128
	s_waitcnt vmcnt(12)
	v_add_u32_e32 v148, 0x40000, v188
	v_cvt_f32_ubyte0_e32 v162, v172
	v_cvt_f32_ubyte1_e32 v163, v172
	v_cvt_f32_ubyte2_e32 v164, v172
	v_cvt_f32_ubyte3_e32 v165, v172
	v_pk_mul_f32 v[162:163], v[162:163], s[48:49] op_sel_hi:[1,0]
	v_pk_mul_f32 v[164:165], v[164:165], s[48:49] op_sel_hi:[1,0]
	v_pk_mul_f32 v[60:61], v[60:61], v[162:163]
	v_pk_mul_f32 v[62:63], v[62:63], v[164:165]
	v_cvt_f32_ubyte0_e32 v162, v173
	v_cvt_f32_ubyte1_e32 v163, v173
	v_cvt_f32_ubyte2_e32 v164, v173
	v_cvt_f32_ubyte3_e32 v165, v173
	v_pk_mul_f32 v[162:163], v[162:163], s[48:49] op_sel_hi:[1,0]
	v_pk_mul_f32 v[164:165], v[164:165], s[48:49] op_sel_hi:[1,0]
	v_pk_mul_f32 v[56:57], v[56:57], v[162:163]
	v_pk_mul_f32 v[58:59], v[58:59], v[164:165]
	v_cvt_pk_bf16_f32 v60, v60, v61
	v_cvt_pk_bf16_f32 v61, v62, v63
	v_cvt_pk_bf16_f32 v62, v56, v57
	v_cvt_pk_bf16_f32 v63, v58, v59
	global_store_dwordx4 v148, v[60:63], s[20:21]
	v_cvt_f32_ubyte0_e32 v162, v174
	v_cvt_f32_ubyte1_e32 v163, v174
	v_cvt_f32_ubyte2_e32 v164, v174
	v_cvt_f32_ubyte3_e32 v165, v174
	v_pk_mul_f32 v[162:163], v[162:163], s[48:49] op_sel_hi:[1,0]
	v_pk_mul_f32 v[164:165], v[164:165], s[48:49] op_sel_hi:[1,0]
	v_pk_mul_f32 v[52:53], v[52:53], v[162:163]
	v_pk_mul_f32 v[54:55], v[54:55], v[164:165]
	v_cvt_f32_ubyte0_e32 v162, v175
	v_cvt_f32_ubyte1_e32 v163, v175
	v_cvt_f32_ubyte2_e32 v164, v175
	v_cvt_f32_ubyte3_e32 v165, v175
	v_pk_mul_f32 v[162:163], v[162:163], s[48:49] op_sel_hi:[1,0]
	v_pk_mul_f32 v[164:165], v[164:165], s[48:49] op_sel_hi:[1,0]
	v_pk_mul_f32 v[48:49], v[48:49], v[162:163]
	v_pk_mul_f32 v[50:51], v[50:51], v[164:165]
	v_cvt_pk_bf16_f32 v52, v52, v53
	v_cvt_pk_bf16_f32 v53, v54, v55
	v_cvt_pk_bf16_f32 v54, v48, v49
	v_cvt_pk_bf16_f32 v55, v50, v51
	global_store_dwordx4 v148, v[52:55], s[20:21] offset:256
	s_waitcnt vmcnt(10)
	v_add_u32_e32 v149, 0x48000, v188
	v_cvt_f32_ubyte0_e32 v162, v176
	v_cvt_f32_ubyte1_e32 v163, v176
	v_cvt_f32_ubyte2_e32 v164, v176
	v_cvt_f32_ubyte3_e32 v165, v176
	v_pk_mul_f32 v[162:163], v[162:163], s[48:49] op_sel_hi:[1,0]
	v_pk_mul_f32 v[164:165], v[164:165], s[48:49] op_sel_hi:[1,0]
	v_pk_mul_f32 v[44:45], v[44:45], v[162:163]
	v_pk_mul_f32 v[46:47], v[46:47], v[164:165]
	v_cvt_f32_ubyte0_e32 v162, v177
	v_cvt_f32_ubyte1_e32 v163, v177
	v_cvt_f32_ubyte2_e32 v164, v177
	v_cvt_f32_ubyte3_e32 v165, v177
	v_pk_mul_f32 v[162:163], v[162:163], s[48:49] op_sel_hi:[1,0]
	v_pk_mul_f32 v[164:165], v[164:165], s[48:49] op_sel_hi:[1,0]
	v_pk_mul_f32 v[40:41], v[40:41], v[162:163]
	v_pk_mul_f32 v[42:43], v[42:43], v[164:165]
	v_cvt_pk_bf16_f32 v44, v44, v45
	v_cvt_pk_bf16_f32 v45, v46, v47
	v_cvt_pk_bf16_f32 v46, v40, v41
	v_cvt_pk_bf16_f32 v47, v42, v43
	global_store_dwordx4 v149, v[44:47], s[20:21]
	v_cvt_f32_ubyte0_e32 v162, v178
	v_cvt_f32_ubyte1_e32 v163, v178
	v_cvt_f32_ubyte2_e32 v164, v178
	v_cvt_f32_ubyte3_e32 v165, v178
	v_pk_mul_f32 v[162:163], v[162:163], s[48:49] op_sel_hi:[1,0]
	v_pk_mul_f32 v[164:165], v[164:165], s[48:49] op_sel_hi:[1,0]
	v_pk_mul_f32 v[36:37], v[36:37], v[162:163]
	v_pk_mul_f32 v[38:39], v[38:39], v[164:165]
	v_cvt_f32_ubyte0_e32 v162, v179
	v_cvt_f32_ubyte1_e32 v163, v179
	v_cvt_f32_ubyte2_e32 v164, v179
	v_cvt_f32_ubyte3_e32 v165, v179
	v_pk_mul_f32 v[162:163], v[162:163], s[48:49] op_sel_hi:[1,0]
	v_pk_mul_f32 v[164:165], v[164:165], s[48:49] op_sel_hi:[1,0]
	v_pk_mul_f32 v[32:33], v[32:33], v[162:163]
	v_pk_mul_f32 v[34:35], v[34:35], v[164:165]
	v_cvt_pk_bf16_f32 v36, v36, v37
	v_cvt_pk_bf16_f32 v37, v38, v39
	v_cvt_pk_bf16_f32 v38, v32, v33
	v_cvt_pk_bf16_f32 v39, v34, v35
	global_store_dwordx4 v149, v[36:39], s[20:21] offset:256
	s_waitcnt vmcnt(8)
	v_add_u32_e32 v148, 0x50000, v188
	v_cvt_f32_ubyte0_e32 v162, v180
	v_cvt_f32_ubyte1_e32 v163, v180
	v_cvt_f32_ubyte2_e32 v164, v180
	v_cvt_f32_ubyte3_e32 v165, v180
	v_pk_mul_f32 v[162:163], v[162:163], s[48:49] op_sel_hi:[1,0]
	v_pk_mul_f32 v[164:165], v[164:165], s[48:49] op_sel_hi:[1,0]
	v_pk_mul_f32 v[28:29], v[28:29], v[162:163]
	v_pk_mul_f32 v[30:31], v[30:31], v[164:165]
	v_cvt_f32_ubyte0_e32 v162, v181
	v_cvt_f32_ubyte1_e32 v163, v181
	v_cvt_f32_ubyte2_e32 v164, v181
	v_cvt_f32_ubyte3_e32 v165, v181
	v_pk_mul_f32 v[162:163], v[162:163], s[48:49] op_sel_hi:[1,0]
	v_pk_mul_f32 v[164:165], v[164:165], s[48:49] op_sel_hi:[1,0]
	v_pk_mul_f32 v[24:25], v[24:25], v[162:163]
	v_pk_mul_f32 v[26:27], v[26:27], v[164:165]
	v_cvt_pk_bf16_f32 v28, v28, v29
	v_cvt_pk_bf16_f32 v29, v30, v31
	v_cvt_pk_bf16_f32 v30, v24, v25
	v_cvt_pk_bf16_f32 v31, v26, v27
	global_store_dwordx4 v148, v[28:31], s[20:21]
	v_cvt_f32_ubyte0_e32 v162, v182
	v_cvt_f32_ubyte1_e32 v163, v182
	v_cvt_f32_ubyte2_e32 v164, v182
	v_cvt_f32_ubyte3_e32 v165, v182
	v_pk_mul_f32 v[162:163], v[162:163], s[48:49] op_sel_hi:[1,0]
	v_pk_mul_f32 v[164:165], v[164:165], s[48:49] op_sel_hi:[1,0]
	v_pk_mul_f32 v[20:21], v[20:21], v[162:163]
	v_pk_mul_f32 v[22:23], v[22:23], v[164:165]
	v_cvt_f32_ubyte0_e32 v162, v183
	v_cvt_f32_ubyte1_e32 v163, v183
	v_cvt_f32_ubyte2_e32 v164, v183
	v_cvt_f32_ubyte3_e32 v165, v183
	v_pk_mul_f32 v[162:163], v[162:163], s[48:49] op_sel_hi:[1,0]
	v_pk_mul_f32 v[164:165], v[164:165], s[48:49] op_sel_hi:[1,0]
	v_pk_mul_f32 v[16:17], v[16:17], v[162:163]
	v_pk_mul_f32 v[18:19], v[18:19], v[164:165]
	v_cvt_pk_bf16_f32 v20, v20, v21
	v_cvt_pk_bf16_f32 v21, v22, v23
	v_cvt_pk_bf16_f32 v22, v16, v17
	v_cvt_pk_bf16_f32 v23, v18, v19
	global_store_dwordx4 v148, v[20:23], s[20:21] offset:256
	s_waitcnt vmcnt(6)
	v_add_u32_e32 v149, 0x58000, v188
	v_cvt_f32_ubyte0_e32 v162, v184
	v_cvt_f32_ubyte1_e32 v163, v184
	v_cvt_f32_ubyte2_e32 v164, v184
	v_cvt_f32_ubyte3_e32 v165, v184
	v_pk_mul_f32 v[162:163], v[162:163], s[48:49] op_sel_hi:[1,0]
	v_pk_mul_f32 v[164:165], v[164:165], s[48:49] op_sel_hi:[1,0]
	v_pk_mul_f32 v[12:13], v[12:13], v[162:163]
	v_pk_mul_f32 v[14:15], v[14:15], v[164:165]
	v_cvt_f32_ubyte0_e32 v162, v185
	v_cvt_f32_ubyte1_e32 v163, v185
	v_cvt_f32_ubyte2_e32 v164, v185
	v_cvt_f32_ubyte3_e32 v165, v185
	v_pk_mul_f32 v[162:163], v[162:163], s[48:49] op_sel_hi:[1,0]
	v_pk_mul_f32 v[164:165], v[164:165], s[48:49] op_sel_hi:[1,0]
	v_pk_mul_f32 v[8:9], v[8:9], v[162:163]
	v_pk_mul_f32 v[10:11], v[10:11], v[164:165]
	v_cvt_pk_bf16_f32 v12, v12, v13
	v_cvt_pk_bf16_f32 v13, v14, v15
	v_cvt_pk_bf16_f32 v14, v8, v9
	v_cvt_pk_bf16_f32 v15, v10, v11
	global_store_dwordx4 v149, v[12:15], s[20:21]
	v_cvt_f32_ubyte0_e32 v162, v186
	v_cvt_f32_ubyte1_e32 v163, v186
	v_cvt_f32_ubyte2_e32 v164, v186
	v_cvt_f32_ubyte3_e32 v165, v186
	v_pk_mul_f32 v[162:163], v[162:163], s[48:49] op_sel_hi:[1,0]
	v_pk_mul_f32 v[164:165], v[164:165], s[48:49] op_sel_hi:[1,0]
	v_pk_mul_f32 v[4:5], v[4:5], v[162:163]
	v_pk_mul_f32 v[6:7], v[6:7], v[164:165]
	v_cvt_f32_ubyte0_e32 v162, v187
	v_cvt_f32_ubyte1_e32 v163, v187
	v_cvt_f32_ubyte2_e32 v164, v187
	v_cvt_f32_ubyte3_e32 v165, v187
	v_pk_mul_f32 v[162:163], v[162:163], s[48:49] op_sel_hi:[1,0]
	v_pk_mul_f32 v[164:165], v[164:165], s[48:49] op_sel_hi:[1,0]
	v_pk_mul_f32 v[0:1], v[0:1], v[162:163]
	v_pk_mul_f32 v[2:3], v[2:3], v[164:165]
	v_cvt_pk_bf16_f32 v4, v4, v5
	v_cvt_pk_bf16_f32 v5, v6, v7
	v_cvt_pk_bf16_f32 v6, v0, v1
	v_cvt_pk_bf16_f32 v7, v2, v3
	global_store_dwordx4 v149, v[4:7], s[20:21] offset:256
	s_and_b64 vcc, exec, s[0:1]
	s_mov_b64 s[0:1], -1
	s_cbranch_vccnz .LBB0_467
	s_andn2_b64 vcc, exec, s[26:27]
	s_cbranch_vccnz .LBB0_466
	s_barrier
	s_branch .LBB0_466

.LBB0_784:
	v_and_b32_e32 v218, 3, v209
	v_bfe_u32 v219, v209, 4, 2
	v_and_or_b32 v219, v209, 12, v219
	v_lshl_or_b32 v207, v218, 4, v219
	v_lshlrev_b32_e32 v207, 2, v207
	v_and_or_b32 v219, v176, -16, v219
	v_and_b32_e32 v220, 0x60, v178
	v_lshl_or_b32 v220, v218, 3, v220
	v_lshl_add_u32 v219, s73, 8, v219
	v_lshl_or_b32 v220, s74, 8, v220
	v_lshlrev_b32_e32 v219, 11, v219
	v_lshl_add_u32 v198, v220, 1, v219
	v_mov_b32_e32 v199, v198
	v_lshrrev_b32_e32 v200, 1, v199
	global_load_dwordx2 v[182:183], v200, s[66:67]
	global_load_dwordx2 v[184:185], v200, s[66:67] offset:128
	global_load_dwordx4 v[128:131], v199, s[20:21]
	global_load_dwordx4 v[132:135], v199, s[20:21] offset:256
	v_add_u32_e32 v201, 0x8000, v198
	v_lshrrev_b32_e32 v204, 1, v201
	global_load_dwordx2 v[186:187], v204, s[66:67]
	global_load_dwordx2 v[188:189], v204, s[66:67] offset:128
	global_load_dwordx4 v[136:139], v201, s[20:21]
	global_load_dwordx4 v[140:143], v201, s[20:21] offset:256
	v_add_u32_e32 v199, 0x10000, v198
	v_lshrrev_b32_e32 v200, 1, v199
	global_load_dwordx2 v[190:191], v200, s[66:67]
	global_load_dwordx2 v[192:193], v200, s[66:67] offset:128
	global_load_dwordx4 v[160:163], v199, s[20:21]
	global_load_dwordx4 v[164:167], v199, s[20:21] offset:256
	v_add_u32_e32 v201, 0x18000, v198
	v_lshrrev_b32_e32 v204, 1, v201
	global_load_dwordx2 v[194:195], v204, s[66:67]
	global_load_dwordx2 v[196:197], v204, s[66:67] offset:128
	global_load_dwordx4 v[168:171], v201, s[20:21]
	global_load_dwordx4 v[172:175], v201, s[20:21] offset:256
	ds_bpermute_b32 v124, v207, v124
	ds_bpermute_b32 v125, v207, v125
	ds_bpermute_b32 v126, v207, v126
	ds_bpermute_b32 v127, v207, v127
	ds_bpermute_b32 v120, v207, v120
	ds_bpermute_b32 v121, v207, v121
	ds_bpermute_b32 v122, v207, v122
	ds_bpermute_b32 v123, v207, v123
	ds_bpermute_b32 v108, v207, v108
	ds_bpermute_b32 v109, v207, v109
	ds_bpermute_b32 v110, v207, v110
	ds_bpermute_b32 v111, v207, v111
	ds_bpermute_b32 v104, v207, v104
	ds_bpermute_b32 v105, v207, v105
	ds_bpermute_b32 v106, v207, v106
	ds_bpermute_b32 v107, v207, v107
	ds_bpermute_b32 v92, v207, v92
	ds_bpermute_b32 v93, v207, v93
	ds_bpermute_b32 v94, v207, v94
	ds_bpermute_b32 v95, v207, v95
	ds_bpermute_b32 v88, v207, v88
	ds_bpermute_b32 v89, v207, v89
	ds_bpermute_b32 v90, v207, v90
	ds_bpermute_b32 v91, v207, v91
	ds_bpermute_b32 v76, v207, v76
	ds_bpermute_b32 v77, v207, v77
	ds_bpermute_b32 v78, v207, v78
	ds_bpermute_b32 v79, v207, v79
	ds_bpermute_b32 v72, v207, v72
	ds_bpermute_b32 v73, v207, v73
	ds_bpermute_b32 v74, v207, v74
	ds_bpermute_b32 v75, v207, v75
	s_and_b64 vcc, exec, s[38:39]
	s_cbranch_vccz .Lp4_nb
	s_barrier
.Lp4_nb:
	ds_bpermute_b32 v116, v207, v116
	ds_bpermute_b32 v117, v207, v117
	ds_bpermute_b32 v118, v207, v118
	ds_bpermute_b32 v119, v207, v119
	ds_bpermute_b32 v112, v207, v112
	ds_bpermute_b32 v113, v207, v113
	ds_bpermute_b32 v114, v207, v114
	ds_bpermute_b32 v115, v207, v115
	ds_bpermute_b32 v100, v207, v100
	ds_bpermute_b32 v101, v207, v101
	ds_bpermute_b32 v102, v207, v102
	ds_bpermute_b32 v103, v207, v103
	ds_bpermute_b32 v96, v207, v96
	ds_bpermute_b32 v97, v207, v97
	ds_bpermute_b32 v98, v207, v98
	ds_bpermute_b32 v99, v207, v99
	ds_bpermute_b32 v84, v207, v84
	ds_bpermute_b32 v85, v207, v85
	ds_bpermute_b32 v86, v207, v86
	ds_bpermute_b32 v87, v207, v87
	ds_bpermute_b32 v80, v207, v80
	ds_bpermute_b32 v81, v207, v81
	ds_bpermute_b32 v82, v207, v82
	ds_bpermute_b32 v83, v207, v83
	ds_bpermute_b32 v68, v207, v68
	ds_bpermute_b32 v69, v207, v69
	ds_bpermute_b32 v70, v207, v70
	ds_bpermute_b32 v71, v207, v71
	ds_bpermute_b32 v64, v207, v64
	ds_bpermute_b32 v65, v207, v65
	ds_bpermute_b32 v66, v207, v66
	ds_bpermute_b32 v67, v207, v67
	ds_bpermute_b32 v60, v207, v60
	ds_bpermute_b32 v61, v207, v61
	ds_bpermute_b32 v62, v207, v62
	ds_bpermute_b32 v63, v207, v63
	ds_bpermute_b32 v56, v207, v56
	ds_bpermute_b32 v57, v207, v57
	ds_bpermute_b32 v58, v207, v58
	ds_bpermute_b32 v59, v207, v59
	ds_bpermute_b32 v44, v207, v44
	ds_bpermute_b32 v45, v207, v45
	ds_bpermute_b32 v46, v207, v46
	ds_bpermute_b32 v47, v207, v47
	ds_bpermute_b32 v40, v207, v40
	ds_bpermute_b32 v41, v207, v41
	ds_bpermute_b32 v42, v207, v42
	ds_bpermute_b32 v43, v207, v43
	ds_bpermute_b32 v28, v207, v28
	ds_bpermute_b32 v29, v207, v29
	ds_bpermute_b32 v30, v207, v30
	ds_bpermute_b32 v31, v207, v31
	ds_bpermute_b32 v24, v207, v24
	ds_bpermute_b32 v25, v207, v25
	ds_bpermute_b32 v26, v207, v26
	ds_bpermute_b32 v27, v207, v27
	ds_bpermute_b32 v12, v207, v12
	ds_bpermute_b32 v13, v207, v13
	ds_bpermute_b32 v14, v207, v14
	ds_bpermute_b32 v15, v207, v15
	ds_bpermute_b32 v8, v207, v8
	ds_bpermute_b32 v9, v207, v9
	ds_bpermute_b32 v10, v207, v10
	ds_bpermute_b32 v11, v207, v11
	ds_bpermute_b32 v52, v207, v52
	ds_bpermute_b32 v53, v207, v53
	ds_bpermute_b32 v54, v207, v54
	ds_bpermute_b32 v55, v207, v55
	ds_bpermute_b32 v48, v207, v48
	ds_bpermute_b32 v49, v207, v49
	ds_bpermute_b32 v50, v207, v50
	ds_bpermute_b32 v51, v207, v51
	ds_bpermute_b32 v36, v207, v36
	ds_bpermute_b32 v37, v207, v37
	ds_bpermute_b32 v38, v207, v38
	ds_bpermute_b32 v39, v207, v39
	ds_bpermute_b32 v32, v207, v32
	ds_bpermute_b32 v33, v207, v33
	ds_bpermute_b32 v34, v207, v34
	ds_bpermute_b32 v35, v207, v35
	ds_bpermute_b32 v20, v207, v20
	ds_bpermute_b32 v21, v207, v21
	ds_bpermute_b32 v22, v207, v22
	ds_bpermute_b32 v23, v207, v23
	ds_bpermute_b32 v16, v207, v16
	ds_bpermute_b32 v17, v207, v17
	ds_bpermute_b32 v18, v207, v18
	ds_bpermute_b32 v19, v207, v19
	ds_bpermute_b32 v4, v207, v4
	ds_bpermute_b32 v5, v207, v5
	ds_bpermute_b32 v6, v207, v6
	ds_bpermute_b32 v7, v207, v7
	ds_bpermute_b32 v0, v207, v0
	ds_bpermute_b32 v1, v207, v1
	ds_bpermute_b32 v2, v207, v2
	ds_bpermute_b32 v3, v207, v3
	s_waitcnt lgkmcnt(0)
	s_waitcnt vmcnt(12)
	v_mov_b32_e32 v205, v198
	v_cvt_f32_ubyte0_e32 v210, v182
	v_cvt_f32_ubyte1_e32 v211, v182
	v_cvt_f32_ubyte2_e32 v212, v182
	v_cvt_f32_ubyte3_e32 v213, v182
	v_pk_mul_f32 v[210:211], v[210:211], s[40:41] op_sel_hi:[1,0]
	v_pk_mul_f32 v[212:213], v[212:213], s[40:41] op_sel_hi:[1,0]
	v_lshlrev_b32_e32 v214, 16, v128
	v_and_b32_e32 v215, 0xffff0000, v128
	v_lshlrev_b32_e32 v216, 16, v129
	v_and_b32_e32 v217, 0xffff0000, v129
	v_pk_fma_f32 v[124:125], v[124:125], v[210:211], v[214:215]
	v_pk_fma_f32 v[126:127], v[126:127], v[212:213], v[216:217]
	v_cvt_f32_ubyte0_e32 v210, v183
	v_cvt_f32_ubyte1_e32 v211, v183
	v_cvt_f32_ubyte2_e32 v212, v183
	v_cvt_f32_ubyte3_e32 v213, v183
	v_pk_mul_f32 v[210:211], v[210:211], s[40:41] op_sel_hi:[1,0]
	v_pk_mul_f32 v[212:213], v[212:213], s[40:41] op_sel_hi:[1,0]
	v_lshlrev_b32_e32 v214, 16, v130
	v_and_b32_e32 v215, 0xffff0000, v130
	v_lshlrev_b32_e32 v216, 16, v131
	v_and_b32_e32 v217, 0xffff0000, v131
	v_pk_fma_f32 v[120:121], v[120:121], v[210:211], v[214:215]
	v_pk_fma_f32 v[122:123], v[122:123], v[212:213], v[216:217]
	v_cvt_pk_bf16_f32 v124, v124, v125
	v_cvt_pk_bf16_f32 v125, v126, v127
	v_cvt_pk_bf16_f32 v126, v120, v121
	v_cvt_pk_bf16_f32 v127, v122, v123
	global_store_dwordx4 v205, v[124:127], s[20:21]
	v_cvt_f32_ubyte0_e32 v210, v184
	v_cvt_f32_ubyte1_e32 v211, v184
	v_cvt_f32_ubyte2_e32 v212, v184
	v_cvt_f32_ubyte3_e32 v213, v184
	v_pk_mul_f32 v[210:211], v[210:211], s[40:41] op_sel_hi:[1,0]
	v_pk_mul_f32 v[212:213], v[212:213], s[40:41] op_sel_hi:[1,0]
	v_lshlrev_b32_e32 v214, 16, v132
	v_and_b32_e32 v215, 0xffff0000, v132
	v_lshlrev_b32_e32 v216, 16, v133
	v_and_b32_e32 v217, 0xffff0000, v133
	v_pk_fma_f32 v[116:117], v[116:117], v[210:211], v[214:215]
	v_pk_fma_f32 v[118:119], v[118:119], v[212:213], v[216:217]
	v_cvt_f32_ubyte0_e32 v210, v185
	v_cvt_f32_ubyte1_e32 v211, v185
	v_cvt_f32_ubyte2_e32 v212, v185
	v_cvt_f32_ubyte3_e32 v213, v185
	v_pk_mul_f32 v[210:211], v[210:211], s[40:41] op_sel_hi:[1,0]
	v_pk_mul_f32 v[212:213], v[212:213], s[40:41] op_sel_hi:[1,0]
	v_lshlrev_b32_e32 v214, 16, v134
	v_and_b32_e32 v215, 0xffff0000, v134
	v_lshlrev_b32_e32 v216, 16, v135
	v_and_b32_e32 v217, 0xffff0000, v135
	v_pk_fma_f32 v[112:113], v[112:113], v[210:211], v[214:215]
	v_pk_fma_f32 v[114:115], v[114:115], v[212:213], v[216:217]
	v_cvt_pk_bf16_f32 v116, v116, v117
	v_cvt_pk_bf16_f32 v117, v118, v119
	v_cvt_pk_bf16_f32 v118, v112, v113
	v_cvt_pk_bf16_f32 v119, v114, v115
	global_store_dwordx4 v205, v[116:119], s[20:21] offset:256
	v_add_u32_e32 v199, 0x40000, v198
	v_lshrrev_b32_e32 v200, 1, v199
	global_load_dwordx2 v[182:183], v200, s[66:67]
	global_load_dwordx2 v[184:185], v200, s[66:67] offset:128
	global_load_dwordx4 v[128:131], v199, s[20:21]
	global_load_dwordx4 v[132:135], v199, s[20:21] offset:256
	s_waitcnt vmcnt(14)
	v_add_u32_e32 v206, 0x8000, v198
	v_cvt_f32_ubyte0_e32 v210, v186
	v_cvt_f32_ubyte1_e32 v211, v186
	v_cvt_f32_ubyte2_e32 v212, v186
	v_cvt_f32_ubyte3_e32 v213, v186
	v_pk_mul_f32 v[210:211], v[210:211], s[40:41] op_sel_hi:[1,0]
	v_pk_mul_f32 v[212:213], v[212:213], s[40:41] op_sel_hi:[1,0]
	v_lshlrev_b32_e32 v214, 16, v136
	v_and_b32_e32 v215, 0xffff0000, v136
	v_lshlrev_b32_e32 v216, 16, v137
	v_and_b32_e32 v217, 0xffff0000, v137
	v_pk_fma_f32 v[108:109], v[108:109], v[210:211], v[214:215]
	v_pk_fma_f32 v[110:111], v[110:111], v[212:213], v[216:217]
	v_cvt_f32_ubyte0_e32 v210, v187
	v_cvt_f32_ubyte1_e32 v211, v187
	v_cvt_f32_ubyte2_e32 v212, v187
	v_cvt_f32_ubyte3_e32 v213, v187
	v_pk_mul_f32 v[210:211], v[210:211], s[40:41] op_sel_hi:[1,0]
	v_pk_mul_f32 v[212:213], v[212:213], s[40:41] op_sel_hi:[1,0]
	v_lshlrev_b32_e32 v214, 16, v138
	v_and_b32_e32 v215, 0xffff0000, v138
	v_lshlrev_b32_e32 v216, 16, v139
	v_and_b32_e32 v217, 0xffff0000, v139
	v_pk_fma_f32 v[104:105], v[104:105], v[210:211], v[214:215]
	v_pk_fma_f32 v[106:107], v[106:107], v[212:213], v[216:217]
	v_cvt_pk_bf16_f32 v108, v108, v109
	v_cvt_pk_bf16_f32 v109, v110, v111
	v_cvt_pk_bf16_f32 v110, v104, v105
	v_cvt_pk_bf16_f32 v111, v106, v107
	global_store_dwordx4 v206, v[108:111], s[20:21]
	v_cvt_f32_ubyte0_e32 v210, v188
	v_cvt_f32_ubyte1_e32 v211, v188
	v_cvt_f32_ubyte2_e32 v212, v188
	v_cvt_f32_ubyte3_e32 v213, v188
	v_pk_mul_f32 v[210:211], v[210:211], s[40:41] op_sel_hi:[1,0]
	v_pk_mul_f32 v[212:213], v[212:213], s[40:41] op_sel_hi:[1,0]
	v_lshlrev_b32_e32 v214, 16, v140
	v_and_b32_e32 v215, 0xffff0000, v140
	v_lshlrev_b32_e32 v216, 16, v141
	v_and_b32_e32 v217, 0xffff0000, v141
	v_pk_fma_f32 v[100:101], v[100:101], v[210:211], v[214:215]
	v_pk_fma_f32 v[102:103], v[102:103], v[212:213], v[216:217]
	v_cvt_f32_ubyte0_e32 v210, v189
	v_cvt_f32_ubyte1_e32 v211, v189
	v_cvt_f32_ubyte2_e32 v212, v189
	v_cvt_f32_ubyte3_e32 v213, v189
	v_pk_mul_f32 v[210:211], v[210:211], s[40:41] op_sel_hi:[1,0]
	v_pk_mul_f32 v[212:213], v[212:213], s[40:41] op_sel_hi:[1,0]
	v_lshlrev_b32_e32 v214, 16, v142
	v_and_b32_e32 v215, 0xffff0000, v142
	v_lshlrev_b32_e32 v216, 16, v143
	v_and_b32_e32 v217, 0xffff0000, v143
	v_pk_fma_f32 v[96:97], v[96:97], v[210:211], v[214:215]
	v_pk_fma_f32 v[98:99], v[98:99], v[212:213], v[216:217]
	v_cvt_pk_bf16_f32 v100, v100, v101
	v_cvt_pk_bf16_f32 v101, v102, v103
	v_cvt_pk_bf16_f32 v102, v96, v97
	v_cvt_pk_bf16_f32 v103, v98, v99
	global_store_dwordx4 v206, v[100:103], s[20:21] offset:256
	v_add_u32_e32 v201, 0x48000, v198
	v_lshrrev_b32_e32 v204, 1, v201
	global_load_dwordx2 v[186:187], v204, s[66:67]
	global_load_dwordx2 v[188:189], v204, s[66:67] offset:128
	global_load_dwordx4 v[136:139], v201, s[20:21]
	global_load_dwordx4 v[140:143], v201, s[20:21] offset:256
	s_waitcnt vmcnt(16)
	v_add_u32_e32 v205, 0x10000, v198
	v_cvt_f32_ubyte0_e32 v210, v190
	v_cvt_f32_ubyte1_e32 v211, v190
	v_cvt_f32_ubyte2_e32 v212, v190
	v_cvt_f32_ubyte3_e32 v213, v190
	v_pk_mul_f32 v[210:211], v[210:211], s[40:41] op_sel_hi:[1,0]
	v_pk_mul_f32 v[212:213], v[212:213], s[40:41] op_sel_hi:[1,0]
	v_lshlrev_b32_e32 v214, 16, v160
	v_and_b32_e32 v215, 0xffff0000, v160
	v_lshlrev_b32_e32 v216, 16, v161
	v_and_b32_e32 v217, 0xffff0000, v161
	v_pk_fma_f32 v[92:93], v[92:93], v[210:211], v[214:215]
	v_pk_fma_f32 v[94:95], v[94:95], v[212:213], v[216:217]
	v_cvt_f32_ubyte0_e32 v210, v191
	v_cvt_f32_ubyte1_e32 v211, v191
	v_cvt_f32_ubyte2_e32 v212, v191
	v_cvt_f32_ubyte3_e32 v213, v191
	v_pk_mul_f32 v[210:211], v[210:211], s[40:41] op_sel_hi:[1,0]
	v_pk_mul_f32 v[212:213], v[212:213], s[40:41] op_sel_hi:[1,0]
	v_lshlrev_b32_e32 v214, 16, v162
	v_and_b32_e32 v215, 0xffff0000, v162
	v_lshlrev_b32_e32 v216, 16, v163
	v_and_b32_e32 v217, 0xffff0000, v163
	v_pk_fma_f32 v[88:89], v[88:89], v[210:211], v[214:215]
	v_pk_fma_f32 v[90:91], v[90:91], v[212:213], v[216:217]
	v_cvt_pk_bf16_f32 v92, v92, v93
	v_cvt_pk_bf16_f32 v93, v94, v95
	v_cvt_pk_bf16_f32 v94, v88, v89
	v_cvt_pk_bf16_f32 v95, v90, v91
	global_store_dwordx4 v205, v[92:95], s[20:21]
	v_cvt_f32_ubyte0_e32 v210, v192
	v_cvt_f32_ubyte1_e32 v211, v192
	v_cvt_f32_ubyte2_e32 v212, v192
	v_cvt_f32_ubyte3_e32 v213, v192
	v_pk_mul_f32 v[210:211], v[210:211], s[40:41] op_sel_hi:[1,0]
	v_pk_mul_f32 v[212:213], v[212:213], s[40:41] op_sel_hi:[1,0]
	v_lshlrev_b32_e32 v214, 16, v164
	v_and_b32_e32 v215, 0xffff0000, v164
	v_lshlrev_b32_e32 v216, 16, v165
	v_and_b32_e32 v217, 0xffff0000, v165
	v_pk_fma_f32 v[84:85], v[84:85], v[210:211], v[214:215]
	v_pk_fma_f32 v[86:87], v[86:87], v[212:213], v[216:217]
	v_cvt_f32_ubyte0_e32 v210, v193
	v_cvt_f32_ubyte1_e32 v211, v193
	v_cvt_f32_ubyte2_e32 v212, v193
	v_cvt_f32_ubyte3_e32 v213, v193
	v_pk_mul_f32 v[210:211], v[210:211], s[40:41] op_sel_hi:[1,0]
	v_pk_mul_f32 v[212:213], v[212:213], s[40:41] op_sel_hi:[1,0]
	v_lshlrev_b32_e32 v214, 16, v166
	v_and_b32_e32 v215, 0xffff0000, v166
	v_lshlrev_b32_e32 v216, 16, v167
	v_and_b32_e32 v217, 0xffff0000, v167
	v_pk_fma_f32 v[80:81], v[80:81], v[210:211], v[214:215]
	v_pk_fma_f32 v[82:83], v[82:83], v[212:213], v[216:217]
	v_cvt_pk_bf16_f32 v84, v84, v85
	v_cvt_pk_bf16_f32 v85, v86, v87
	v_cvt_pk_bf16_f32 v86, v80, v81
	v_cvt_pk_bf16_f32 v87, v82, v83
	global_store_dwordx4 v205, v[84:87], s[20:21] offset:256
	v_add_u32_e32 v199, 0x50000, v198
	v_lshrrev_b32_e32 v200, 1, v199
	global_load_dwordx2 v[190:191], v200, s[66:67]
	global_load_dwordx2 v[192:193], v200, s[66:67] offset:128
	global_load_dwordx4 v[160:163], v199, s[20:21]
	global_load_dwordx4 v[164:167], v199, s[20:21] offset:256
	s_waitcnt vmcnt(18)
	v_add_u32_e32 v206, 0x18000, v198
	v_cvt_f32_ubyte0_e32 v210, v194
	v_cvt_f32_ubyte1_e32 v211, v194
	v_cvt_f32_ubyte2_e32 v212, v194
	v_cvt_f32_ubyte3_e32 v213, v194
	v_pk_mul_f32 v[210:211], v[210:211], s[40:41] op_sel_hi:[1,0]
	v_pk_mul_f32 v[212:213], v[212:213], s[40:41] op_sel_hi:[1,0]
	v_lshlrev_b32_e32 v214, 16, v168
	v_and_b32_e32 v215, 0xffff0000, v168
	v_lshlrev_b32_e32 v216, 16, v169
	v_and_b32_e32 v217, 0xffff0000, v169
	v_pk_fma_f32 v[76:77], v[76:77], v[210:211], v[214:215]
	v_pk_fma_f32 v[78:79], v[78:79], v[212:213], v[216:217]
	v_cvt_f32_ubyte0_e32 v210, v195
	v_cvt_f32_ubyte1_e32 v211, v195
	v_cvt_f32_ubyte2_e32 v212, v195
	v_cvt_f32_ubyte3_e32 v213, v195
	v_pk_mul_f32 v[210:211], v[210:211], s[40:41] op_sel_hi:[1,0]
	v_pk_mul_f32 v[212:213], v[212:213], s[40:41] op_sel_hi:[1,0]
	v_lshlrev_b32_e32 v214, 16, v170
	v_and_b32_e32 v215, 0xffff0000, v170
	v_lshlrev_b32_e32 v216, 16, v171
	v_and_b32_e32 v217, 0xffff0000, v171
	v_pk_fma_f32 v[72:73], v[72:73], v[210:211], v[214:215]
	v_pk_fma_f32 v[74:75], v[74:75], v[212:213], v[216:217]
	v_cvt_pk_bf16_f32 v76, v76, v77
	v_cvt_pk_bf16_f32 v77, v78, v79
	v_cvt_pk_bf16_f32 v78, v72, v73
	v_cvt_pk_bf16_f32 v79, v74, v75
	global_store_dwordx4 v206, v[76:79], s[20:21]
	v_cvt_f32_ubyte0_e32 v210, v196
	v_cvt_f32_ubyte1_e32 v211, v196
	v_cvt_f32_ubyte2_e32 v212, v196
	v_cvt_f32_ubyte3_e32 v213, v196
	v_pk_mul_f32 v[210:211], v[210:211], s[40:41] op_sel_hi:[1,0]
	v_pk_mul_f32 v[212:213], v[212:213], s[40:41] op_sel_hi:[1,0]
	v_lshlrev_b32_e32 v214, 16, v172
	v_and_b32_e32 v215, 0xffff0000, v172
	v_lshlrev_b32_e32 v216, 16, v173
	v_and_b32_e32 v217, 0xffff0000, v173
	v_pk_fma_f32 v[68:69], v[68:69], v[210:211], v[214:215]
	v_pk_fma_f32 v[70:71], v[70:71], v[212:213], v[216:217]
	v_cvt_f32_ubyte0_e32 v210, v197
	v_cvt_f32_ubyte1_e32 v211, v197
	v_cvt_f32_ubyte2_e32 v212, v197
	v_cvt_f32_ubyte3_e32 v213, v197
	v_pk_mul_f32 v[210:211], v[210:211], s[40:41] op_sel_hi:[1,0]
	v_pk_mul_f32 v[212:213], v[212:213], s[40:41] op_sel_hi:[1,0]
	v_lshlrev_b32_e32 v214, 16, v174
	v_and_b32_e32 v215, 0xffff0000, v174
	v_lshlrev_b32_e32 v216, 16, v175
	v_and_b32_e32 v217, 0xffff0000, v175
	v_pk_fma_f32 v[64:65], v[64:65], v[210:211], v[214:215]
	v_pk_fma_f32 v[66:67], v[66:67], v[212:213], v[216:217]
	v_cvt_pk_bf16_f32 v68, v68, v69
	v_cvt_pk_bf16_f32 v69, v70, v71
	v_cvt_pk_bf16_f32 v70, v64, v65
	v_cvt_pk_bf16_f32 v71, v66, v67
	global_store_dwordx4 v206, v[68:71], s[20:21] offset:256
	v_add_u32_e32 v201, 0x58000, v198
	v_lshrrev_b32_e32 v204, 1, v201
	global_load_dwordx2 v[194:195], v204, s[66:67]
	global_load_dwordx2 v[196:197], v204, s[66:67] offset:128
	global_load_dwordx4 v[168:171], v201, s[20:21]
	global_load_dwordx4 v[172:175], v201, s[20:21] offset:256
	s_waitcnt vmcnt(18)
	v_add_u32_e32 v205, 0x40000, v198
	v_cvt_f32_ubyte0_e32 v210, v182
	v_cvt_f32_ubyte1_e32 v211, v182
	v_cvt_f32_ubyte2_e32 v212, v182
	v_cvt_f32_ubyte3_e32 v213, v182
	v_pk_mul_f32 v[210:211], v[210:211], s[40:41] op_sel_hi:[1,0]
	v_pk_mul_f32 v[212:213], v[212:213], s[40:41] op_sel_hi:[1,0]
	v_lshlrev_b32_e32 v214, 16, v128
	v_and_b32_e32 v215, 0xffff0000, v128
	v_lshlrev_b32_e32 v216, 16, v129
	v_and_b32_e32 v217, 0xffff0000, v129
	v_pk_fma_f32 v[60:61], v[60:61], v[210:211], v[214:215]
	v_pk_fma_f32 v[62:63], v[62:63], v[212:213], v[216:217]
	v_cvt_f32_ubyte0_e32 v210, v183
	v_cvt_f32_ubyte1_e32 v211, v183
	v_cvt_f32_ubyte2_e32 v212, v183
	v_cvt_f32_ubyte3_e32 v213, v183
	v_pk_mul_f32 v[210:211], v[210:211], s[40:41] op_sel_hi:[1,0]
	v_pk_mul_f32 v[212:213], v[212:213], s[40:41] op_sel_hi:[1,0]
	v_lshlrev_b32_e32 v214, 16, v130
	v_and_b32_e32 v215, 0xffff0000, v130
	v_lshlrev_b32_e32 v216, 16, v131
	v_and_b32_e32 v217, 0xffff0000, v131
	v_pk_fma_f32 v[56:57], v[56:57], v[210:211], v[214:215]
	v_pk_fma_f32 v[58:59], v[58:59], v[212:213], v[216:217]
	v_cvt_pk_bf16_f32 v60, v60, v61
	v_cvt_pk_bf16_f32 v61, v62, v63
	v_cvt_pk_bf16_f32 v62, v56, v57
	v_cvt_pk_bf16_f32 v63, v58, v59
	global_store_dwordx4 v205, v[60:63], s[20:21]
	v_cvt_f32_ubyte0_e32 v210, v184
	v_cvt_f32_ubyte1_e32 v211, v184
	v_cvt_f32_ubyte2_e32 v212, v184
	v_cvt_f32_ubyte3_e32 v213, v184
	v_pk_mul_f32 v[210:211], v[210:211], s[40:41] op_sel_hi:[1,0]
	v_pk_mul_f32 v[212:213], v[212:213], s[40:41] op_sel_hi:[1,0]
	v_lshlrev_b32_e32 v214, 16, v132
	v_and_b32_e32 v215, 0xffff0000, v132
	v_lshlrev_b32_e32 v216, 16, v133
	v_and_b32_e32 v217, 0xffff0000, v133
	v_pk_fma_f32 v[52:53], v[52:53], v[210:211], v[214:215]
	v_pk_fma_f32 v[54:55], v[54:55], v[212:213], v[216:217]
	v_cvt_f32_ubyte0_e32 v210, v185
	v_cvt_f32_ubyte1_e32 v211, v185
	v_cvt_f32_ubyte2_e32 v212, v185
	v_cvt_f32_ubyte3_e32 v213, v185
	v_pk_mul_f32 v[210:211], v[210:211], s[40:41] op_sel_hi:[1,0]
	v_pk_mul_f32 v[212:213], v[212:213], s[40:41] op_sel_hi:[1,0]
	v_lshlrev_b32_e32 v214, 16, v134
	v_and_b32_e32 v215, 0xffff0000, v134
	v_lshlrev_b32_e32 v216, 16, v135
	v_and_b32_e32 v217, 0xffff0000, v135
	v_pk_fma_f32 v[48:49], v[48:49], v[210:211], v[214:215]
	v_pk_fma_f32 v[50:51], v[50:51], v[212:213], v[216:217]
	v_cvt_pk_bf16_f32 v52, v52, v53
	v_cvt_pk_bf16_f32 v53, v54, v55
	v_cvt_pk_bf16_f32 v54, v48, v49
	v_cvt_pk_bf16_f32 v55, v50, v51
	global_store_dwordx4 v205, v[52:55], s[20:21] offset:256
	s_waitcnt vmcnt(14)
	v_add_u32_e32 v206, 0x48000, v198
	v_cvt_f32_ubyte0_e32 v210, v186
	v_cvt_f32_ubyte1_e32 v211, v186
	v_cvt_f32_ubyte2_e32 v212, v186
	v_cvt_f32_ubyte3_e32 v213, v186
	v_pk_mul_f32 v[210:211], v[210:211], s[40:41] op_sel_hi:[1,0]
	v_pk_mul_f32 v[212:213], v[212:213], s[40:41] op_sel_hi:[1,0]
	v_lshlrev_b32_e32 v214, 16, v136
	v_and_b32_e32 v215, 0xffff0000, v136
	v_lshlrev_b32_e32 v216, 16, v137
	v_and_b32_e32 v217, 0xffff0000, v137
	v_pk_fma_f32 v[44:45], v[44:45], v[210:211], v[214:215]
	v_pk_fma_f32 v[46:47], v[46:47], v[212:213], v[216:217]
	v_cvt_f32_ubyte0_e32 v210, v187
	v_cvt_f32_ubyte1_e32 v211, v187
	v_cvt_f32_ubyte2_e32 v212, v187
	v_cvt_f32_ubyte3_e32 v213, v187
	v_pk_mul_f32 v[210:211], v[210:211], s[40:41] op_sel_hi:[1,0]
	v_pk_mul_f32 v[212:213], v[212:213], s[40:41] op_sel_hi:[1,0]
	v_lshlrev_b32_e32 v214, 16, v138
	v_and_b32_e32 v215, 0xffff0000, v138
	v_lshlrev_b32_e32 v216, 16, v139
	v_and_b32_e32 v217, 0xffff0000, v139
	v_pk_fma_f32 v[40:41], v[40:41], v[210:211], v[214:215]
	v_pk_fma_f32 v[42:43], v[42:43], v[212:213], v[216:217]
	v_cvt_pk_bf16_f32 v44, v44, v45
	v_cvt_pk_bf16_f32 v45, v46, v47
	v_cvt_pk_bf16_f32 v46, v40, v41
	v_cvt_pk_bf16_f32 v47, v42, v43
	global_store_dwordx4 v206, v[44:47], s[20:21]
	v_cvt_f32_ubyte0_e32 v210, v188
	v_cvt_f32_ubyte1_e32 v211, v188
	v_cvt_f32_ubyte2_e32 v212, v188
	v_cvt_f32_ubyte3_e32 v213, v188
	v_pk_mul_f32 v[210:211], v[210:211], s[40:41] op_sel_hi:[1,0]
	v_pk_mul_f32 v[212:213], v[212:213], s[40:41] op_sel_hi:[1,0]
	v_lshlrev_b32_e32 v214, 16, v140
	v_and_b32_e32 v215, 0xffff0000, v140
	v_lshlrev_b32_e32 v216, 16, v141
	v_and_b32_e32 v217, 0xffff0000, v141
	v_pk_fma_f32 v[36:37], v[36:37], v[210:211], v[214:215]
	v_pk_fma_f32 v[38:39], v[38:39], v[212:213], v[216:217]
	v_cvt_f32_ubyte0_e32 v210, v189
	v_cvt_f32_ubyte1_e32 v211, v189
	v_cvt_f32_ubyte2_e32 v212, v189
	v_cvt_f32_ubyte3_e32 v213, v189
	v_pk_mul_f32 v[210:211], v[210:211], s[40:41] op_sel_hi:[1,0]
	v_pk_mul_f32 v[212:213], v[212:213], s[40:41] op_sel_hi:[1,0]
	v_lshlrev_b32_e32 v214, 16, v142
	v_and_b32_e32 v215, 0xffff0000, v142
	v_lshlrev_b32_e32 v216, 16, v143
	v_and_b32_e32 v217, 0xffff0000, v143
	v_pk_fma_f32 v[32:33], v[32:33], v[210:211], v[214:215]
	v_pk_fma_f32 v[34:35], v[34:35], v[212:213], v[216:217]
	v_cvt_pk_bf16_f32 v36, v36, v37
	v_cvt_pk_bf16_f32 v37, v38, v39
	v_cvt_pk_bf16_f32 v38, v32, v33
	v_cvt_pk_bf16_f32 v39, v34, v35
	global_store_dwordx4 v206, v[36:39], s[20:21] offset:256
	s_waitcnt vmcnt(10)
	v_add_u32_e32 v205, 0x50000, v198
	v_cvt_f32_ubyte0_e32 v210, v190
	v_cvt_f32_ubyte1_e32 v211, v190
	v_cvt_f32_ubyte2_e32 v212, v190
	v_cvt_f32_ubyte3_e32 v213, v190
	v_pk_mul_f32 v[210:211], v[210:211], s[40:41] op_sel_hi:[1,0]
	v_pk_mul_f32 v[212:213], v[212:213], s[40:41] op_sel_hi:[1,0]
	v_lshlrev_b32_e32 v214, 16, v160
	v_and_b32_e32 v215, 0xffff0000, v160
	v_lshlrev_b32_e32 v216, 16, v161
	v_and_b32_e32 v217, 0xffff0000, v161
	v_pk_fma_f32 v[28:29], v[28:29], v[210:211], v[214:215]
	v_pk_fma_f32 v[30:31], v[30:31], v[212:213], v[216:217]
	v_cvt_f32_ubyte0_e32 v210, v191
	v_cvt_f32_ubyte1_e32 v211, v191
	v_cvt_f32_ubyte2_e32 v212, v191
	v_cvt_f32_ubyte3_e32 v213, v191
	v_pk_mul_f32 v[210:211], v[210:211], s[40:41] op_sel_hi:[1,0]
	v_pk_mul_f32 v[212:213], v[212:213], s[40:41] op_sel_hi:[1,0]
	v_lshlrev_b32_e32 v214, 16, v162
	v_and_b32_e32 v215, 0xffff0000, v162
	v_lshlrev_b32_e32 v216, 16, v163
	v_and_b32_e32 v217, 0xffff0000, v163
	v_pk_fma_f32 v[24:25], v[24:25], v[210:211], v[214:215]
	v_pk_fma_f32 v[26:27], v[26:27], v[212:213], v[216:217]
	v_cvt_pk_bf16_f32 v28, v28, v29
	v_cvt_pk_bf16_f32 v29, v30, v31
	v_cvt_pk_bf16_f32 v30, v24, v25
	v_cvt_pk_bf16_f32 v31, v26, v27
	global_store_dwordx4 v205, v[28:31], s[20:21]
	v_cvt_f32_ubyte0_e32 v210, v192
	v_cvt_f32_ubyte1_e32 v211, v192
	v_cvt_f32_ubyte2_e32 v212, v192
	v_cvt_f32_ubyte3_e32 v213, v192
	v_pk_mul_f32 v[210:211], v[210:211], s[40:41] op_sel_hi:[1,0]
	v_pk_mul_f32 v[212:213], v[212:213], s[40:41] op_sel_hi:[1,0]
	v_lshlrev_b32_e32 v214, 16, v164
	v_and_b32_e32 v215, 0xffff0000, v164
	v_lshlrev_b32_e32 v216, 16, v165
	v_and_b32_e32 v217, 0xffff0000, v165
	v_pk_fma_f32 v[20:21], v[20:21], v[210:211], v[214:215]
	v_pk_fma_f32 v[22:23], v[22:23], v[212:213], v[216:217]
	v_cvt_f32_ubyte0_e32 v210, v193
	v_cvt_f32_ubyte1_e32 v211, v193
	v_cvt_f32_ubyte2_e32 v212, v193
	v_cvt_f32_ubyte3_e32 v213, v193
	v_pk_mul_f32 v[210:211], v[210:211], s[40:41] op_sel_hi:[1,0]
	v_pk_mul_f32 v[212:213], v[212:213], s[40:41] op_sel_hi:[1,0]
	v_lshlrev_b32_e32 v214, 16, v166
	v_and_b32_e32 v215, 0xffff0000, v166
	v_lshlrev_b32_e32 v216, 16, v167
	v_and_b32_e32 v217, 0xffff0000, v167
	v_pk_fma_f32 v[16:17], v[16:17], v[210:211], v[214:215]
	v_pk_fma_f32 v[18:19], v[18:19], v[212:213], v[216:217]
	v_cvt_pk_bf16_f32 v20, v20, v21
	v_cvt_pk_bf16_f32 v21, v22, v23
	v_cvt_pk_bf16_f32 v22, v16, v17
	v_cvt_pk_bf16_f32 v23, v18, v19
	global_store_dwordx4 v205, v[20:23], s[20:21] offset:256
	s_waitcnt vmcnt(6)
	v_add_u32_e32 v206, 0x58000, v198
	v_cvt_f32_ubyte0_e32 v210, v194
	v_cvt_f32_ubyte1_e32 v211, v194
	v_cvt_f32_ubyte2_e32 v212, v194
	v_cvt_f32_ubyte3_e32 v213, v194
	v_pk_mul_f32 v[210:211], v[210:211], s[40:41] op_sel_hi:[1,0]
	v_pk_mul_f32 v[212:213], v[212:213], s[40:41] op_sel_hi:[1,0]
	v_lshlrev_b32_e32 v214, 16, v168
	v_and_b32_e32 v215, 0xffff0000, v168
	v_lshlrev_b32_e32 v216, 16, v169
	v_and_b32_e32 v217, 0xffff0000, v169
	v_pk_fma_f32 v[12:13], v[12:13], v[210:211], v[214:215]
	v_pk_fma_f32 v[14:15], v[14:15], v[212:213], v[216:217]
	v_cvt_f32_ubyte0_e32 v210, v195
	v_cvt_f32_ubyte1_e32 v211, v195
	v_cvt_f32_ubyte2_e32 v212, v195
	v_cvt_f32_ubyte3_e32 v213, v195
	v_pk_mul_f32 v[210:211], v[210:211], s[40:41] op_sel_hi:[1,0]
	v_pk_mul_f32 v[212:213], v[212:213], s[40:41] op_sel_hi:[1,0]
	v_lshlrev_b32_e32 v214, 16, v170
	v_and_b32_e32 v215, 0xffff0000, v170
	v_lshlrev_b32_e32 v216, 16, v171
	v_and_b32_e32 v217, 0xffff0000, v171
	v_pk_fma_f32 v[8:9], v[8:9], v[210:211], v[214:215]
	v_pk_fma_f32 v[10:11], v[10:11], v[212:213], v[216:217]
	v_cvt_pk_bf16_f32 v12, v12, v13
	v_cvt_pk_bf16_f32 v13, v14, v15
	v_cvt_pk_bf16_f32 v14, v8, v9
	v_cvt_pk_bf16_f32 v15, v10, v11
	global_store_dwordx4 v206, v[12:15], s[20:21]
	v_cvt_f32_ubyte0_e32 v210, v196
	v_cvt_f32_ubyte1_e32 v211, v196
	v_cvt_f32_ubyte2_e32 v212, v196
	v_cvt_f32_ubyte3_e32 v213, v196
	v_pk_mul_f32 v[210:211], v[210:211], s[40:41] op_sel_hi:[1,0]
	v_pk_mul_f32 v[212:213], v[212:213], s[40:41] op_sel_hi:[1,0]
	v_lshlrev_b32_e32 v214, 16, v172
	v_and_b32_e32 v215, 0xffff0000, v172
	v_lshlrev_b32_e32 v216, 16, v173
	v_and_b32_e32 v217, 0xffff0000, v173
	v_pk_fma_f32 v[4:5], v[4:5], v[210:211], v[214:215]
	v_pk_fma_f32 v[6:7], v[6:7], v[212:213], v[216:217]
	v_cvt_f32_ubyte0_e32 v210, v197
	v_cvt_f32_ubyte1_e32 v211, v197
	v_cvt_f32_ubyte2_e32 v212, v197
	v_cvt_f32_ubyte3_e32 v213, v197
	v_pk_mul_f32 v[210:211], v[210:211], s[40:41] op_sel_hi:[1,0]
	v_pk_mul_f32 v[212:213], v[212:213], s[40:41] op_sel_hi:[1,0]
	v_lshlrev_b32_e32 v214, 16, v174
	v_and_b32_e32 v215, 0xffff0000, v174
	v_lshlrev_b32_e32 v216, 16, v175
	v_and_b32_e32 v217, 0xffff0000, v175
	v_pk_fma_f32 v[0:1], v[0:1], v[210:211], v[214:215]
	v_pk_fma_f32 v[2:3], v[2:3], v[212:213], v[216:217]
	v_cvt_pk_bf16_f32 v4, v4, v5
	v_cvt_pk_bf16_f32 v5, v6, v7
	v_cvt_pk_bf16_f32 v6, v0, v1
	v_cvt_pk_bf16_f32 v7, v2, v3
	global_store_dwordx4 v206, v[4:7], s[20:21] offset:256
	s_and_b64 vcc, exec, s[0:1]
	s_mov_b64 s[0:1], -1
	s_cbranch_vccnz .LBB0_770
	s_andn2_b64 vcc, exec, s[24:25]
	s_cbranch_vccnz .LBB0_769
	s_barrier
	s_branch .LBB0_769
